# attention no-mask path: weights as e_j*(inclusive suffix product)*carry (14 beta multiplies folded away), reciprocals written to final registers (8 copies removed), exps batched
# speedup vs baseline: 1.0023x; 1.0023x over previous
; #define LAS __attribute__((address_space(3)))
; __device__ __forceinline__ void attn_unit(LAS unsigned char* lds, const bf16_t* Qm, const bf16_t* Km, const bf16_t* VT, const bf16_t* GBm, bf16_t* YB, int b, int hp, int qb) {
;     ...
;         if (k0 < qw + 15 && !__all(Rs == 0.f)) {
;             f32x4 s[4];
; #pragma unroll
;             for (int rb = 0; rb < 4; ++rb) {
;                 const int c = rb >> 1, e = rb & 1;
;                 const int kl = 32 * c + (fr >> 2) * 8 + e * 4 + (fr & 3);
;                 s[rb] = (f32x4){0.f, 0.f, 0.f, 0.f};
; #pragma unroll
;                 for (int ks = 0; ks < 4; ++ks) {
;                     const bf16x8 a = *(const LAS bf16x8*)(KL + kl * 272 + (ks * 32 + fq * 8) * 2);
;                     s[rb] = __builtin_amdgcn_mfma_f32_16x16x32_bf16(a, qf[ks], s[rb], 0, 0, 0);
;                 }
;             }
;             const int qi = qw + fr;
;             float be[2][8], om[2][8];
; #pragma unroll
;             for (int c = 0; c < 2; ++c)
; #pragma unroll
;                 for (int i = 0; i < 8; ++i) {
;                     const float z = s[2 * c + (i >> 2)][i & 3];
;                     const int key = k0 + 32 * c + 8 * fq + i;
;                     const float e = __builtin_amdgcn_exp2f(-fabsf(z));
;                     const float r = __builtin_amdgcn_rcpf(1.0f + e);
;                     const bool pos = z >= 0.f, valid = key < qi;
;                     be[c][i] = valid ? (pos ? r : e * r) : 0.f;
;                     om[c][i] = valid ? (pos ? e * r : r) : 1.f;
;                 }
;             float suf[2][8], Gs[2], Tt[2];
; #pragma unroll
;             for (int c = 0; c < 2; ++c) {
;                 float run = 1.f;
; #pragma unroll
;                 for (int i = 7; i >= 0; --i) { suf[c][i] = run; run *= om[c][i]; }
;                 const float t1 = __shfl(run, (lane + 16) & 63), t2 = __shfl(run, (lane + 32) & 63), t3 = __shfl(run, (lane + 48) & 63);
;                 Gs[c] = (fq < 3 ? t1 : 1.f) * (fq < 2 ? t2 : 1.f) * (fq < 1 ? t3 : 1.f);
;                 Tt[c] = (run * t1) * (t2 * t3);
;             }
.Lattn_nomask:
	ds_read_b128 v[120:123], v116
	ds_read_b128 v[124:127], v116 offset:64
	ds_read_b128 v[128:131], v116 offset:1088
	ds_read_b128 v[132:135], v116 offset:1152
	s_waitcnt lgkmcnt(3)
	v_mfma_f32_16x16x32_bf16 v[120:123], v[120:123], v[0:3], 0
	s_waitcnt lgkmcnt(2)
	v_mfma_f32_16x16x32_bf16 v[120:123], v[124:127], v[4:7], v[120:123]
	ds_read_b128 v[124:127], v116 offset:128
	ds_read_b128 v[136:139], v116 offset:192
	s_waitcnt lgkmcnt(3)
	v_mfma_f32_16x16x32_bf16 v[128:131], v[128:131], v[0:3], 0
	s_waitcnt lgkmcnt(1)
	v_mfma_f32_16x16x32_bf16 v[120:123], v[124:127], v[8:11], v[120:123]
	ds_read_b128 v[124:127], v116 offset:1216
	ds_read_b128 v[140:143], v116 offset:1280
	ds_read_b128 v[144:147], v116 offset:8704
	ds_read_b128 v[148:151], v116 offset:8768
	v_mfma_f32_16x16x32_bf16 v[128:131], v[132:135], v[4:7], v[128:131]
	ds_read_b128 v[132:135], v116 offset:8832
	ds_read_b128 v[152:155], v116 offset:8896
	ds_read_b128 v[156:159], v116 offset:9792
	ds_read_b128 v[160:163], v116 offset:9856
	s_waitcnt lgkmcnt(8)
	v_mfma_f32_16x16x32_bf16 v[120:123], v[136:139], v[12:15], v[120:123]
	ds_read_b128 v[136:139], v116 offset:9920
	ds_read_b128 v[164:167], v116 offset:9984
	s_waitcnt lgkmcnt(9)
	v_mfma_f32_16x16x32_bf16 v[124:127], v[124:127], v[8:11], v[128:131]
	s_nop 3
	v_exp_f32_e32 v97, v120
	s_nop 0
	v_add_f32_e32 v101, 1.0, v97
	s_waitcnt lgkmcnt(7)
	v_mfma_f32_16x16x32_bf16 v[128:131], v[144:147], v[0:3], 0
	v_rcp_f32_e32 v168, v101
	s_nop 0
	v_mul_f32_e32 v101, v97, v168
	s_waitcnt lgkmcnt(6)
	v_mfma_f32_16x16x32_bf16 v[128:131], v[148:151], v[4:7], v[128:131]
	v_mfma_f32_16x16x32_bf16 v[124:127], v[140:143], v[12:15], v[124:127]
	v_exp_f32_e32 v142, v121
	v_exp_f32_e32 v143, v122
	s_waitcnt lgkmcnt(5)
	v_mfma_f32_16x16x32_bf16 v[128:131], v[132:135], v[8:11], v[128:131]
	v_add_f32_e32 v103, 1.0, v142
	v_rcp_f32_e32 v103, v103
	s_waitcnt lgkmcnt(3)
	v_mfma_f32_16x16x32_bf16 v[132:135], v[156:159], v[0:3], 0
	v_add_f32_e32 v120, 1.0, v143
	v_rcp_f32_e32 v120, v120
	s_waitcnt lgkmcnt(2)
	v_mfma_f32_16x16x32_bf16 v[132:135], v[160:163], v[4:7], v[132:135]
	s_waitcnt lgkmcnt(1)
	v_mfma_f32_16x16x32_bf16 v[132:135], v[136:139], v[8:11], v[132:135]
	v_exp_f32_e32 v144, v123
	v_exp_f32_e32 v145, v124
	v_add_f32_e32 v121, 1.0, v144
	v_rcp_f32_e32 v121, v121
	v_add_f32_e32 v122, 1.0, v145
	v_rcp_f32_e32 v122, v122
	v_mfma_f32_16x16x32_bf16 v[128:131], v[152:155], v[12:15], v[128:131]
	s_nop 0
	s_nop 0
	v_exp_f32_e32 v146, v125
	s_nop 0
	v_add_f32_e32 v123, 1.0, v146
	v_rcp_f32_e32 v123, v123
	s_nop 0
	s_nop 0
	v_exp_f32_e32 v138, v128
	v_exp_f32_e32 v131, v131
	v_exp_f32_e32 v126, v126
	s_nop 0
	v_add_f32_e32 v124, 1.0, v126
	v_rcp_f32_e32 v124, v124
	s_waitcnt lgkmcnt(0)
	v_mfma_f32_16x16x32_bf16 v[132:135], v[164:167], v[12:15], v[132:135]
	v_exp_f32_e32 v127, v127
	s_nop 0
	v_add_f32_e32 v125, 1.0, v127
	v_rcp_f32_e32 v147, v125
	v_add_f32_e32 v136, 1.0, v138
	v_rcp_f32_e32 v140, v136
	v_exp_f32_e32 v129, v129
	v_exp_f32_e32 v130, v130
	v_mul_f32_e32 v128, v138, v140
	v_add_f32_e32 v125, 1.0, v129
	v_add_f32_e32 v136, 1.0, v130
	v_add_f32_e32 v137, 1.0, v131
	v_rcp_f32_e32 v125, v125
	v_rcp_f32_e32 v141, v136
	v_rcp_f32_e32 v148, v137
	v_mul_f32_e32 v153, v147, v124
	v_mul_f32_e32 v154, v123, v153
	v_mul_f32_e32 v155, v122, v154
	v_exp_f32_e32 v132, v132
	v_exp_f32_e32 v133, v133
	v_exp_f32_e32 v134, v134
	v_exp_f32_e32 v99, v135
	v_mul_f32_e32 v156, v121, v155
	v_add_f32_e32 v136, 1.0, v132
	v_add_f32_e32 v137, 1.0, v133
	v_add_f32_e32 v138, 1.0, v134
	v_add_f32_e32 v139, 1.0, v99
	v_rcp_f32_e32 v149, v136
	v_rcp_f32_e32 v150, v137
	v_rcp_f32_e32 v152, v138
	v_rcp_f32_e32 v151, v139
	v_mul_f32_e32 v157, v120, v156
	v_mul_f32_e32 v103, v103, v157
	v_mul_f32_e32 v136, v168, v103
	v_or_b32_e32 v135, v105, v107
	v_lshlrev_b32_e32 v135, 2, v135
	v_xor_b32_e32 v135, 0x80, v135
	v_mul_f32_e32 v152, v151, v152
	ds_bpermute_b32 v137, v135, v136
	ds_bpermute_b32 v138, v118, v136
	v_mul_f32_e32 v150, v150, v152
	v_mul_f32_e32 v149, v149, v150
	v_mul_f32_e32 v148, v148, v149
	v_mul_f32_e32 v158, v141, v148
	v_mul_f32_e32 v159, v125, v158
	ds_bpermute_b32 v139, v119, v136
	s_waitcnt lgkmcnt(2)
	v_cndmask_b32_e64 v97, 1.0, v137, s[10:11]
	s_waitcnt lgkmcnt(1)
; #define LAS __attribute__((address_space(3)))
; __device__ __forceinline__ unsigned cvt_pk_bf16(float lo, float hi) { unsigned r; asm volatile("v_cvt_pk_bf16_f32 %0, %1, %2" : "=v"(r) : "v"(lo), "v"(hi)); return r; }
; __device__ __forceinline__ void attn_unit(LAS unsigned char* lds, const bf16_t* Qm, const bf16_t* Km, const bf16_t* VT, const bf16_t* GBm, bf16_t* YB, int b, int hp, int qb) {
;     ...
;                 const float t1 = __shfl(run, (lane + 16) & 63), t2 = __shfl(run, (lane + 32) & 63), t3 = __shfl(run, (lane + 48) & 63);
;                 Gs[c] = (fq < 3 ? t1 : 1.f) * (fq < 2 ? t2 : 1.f) * (fq < 1 ? t3 : 1.f);
;                 Tt[c] = (run * t1) * (t2 * t3);
;             }
;             bf16x8 pf[2];
; #pragma unroll
;             for (int c = 0; c < 2; ++c) {
;                 const float basec = Rs * Gs[c] * (c == 0 ? Tt[1] : 1.f);
;                 float w[8];
; #pragma unroll
;                 for (int i = 0; i < 8; ++i) w[i] = be[c][i] * (suf[c][i] * basec);
;                 u32x4 pw; pw.x = cvt_pk_bf16(w[0], w[1]); pw.y = cvt_pk_bf16(w[2], w[3]); pw.z = cvt_pk_bf16(w[4], w[5]); pw.w = cvt_pk_bf16(w[6], w[7]);
;                 pf[c] = __builtin_bit_cast(bf16x8, pw);
;             }
;             Rs *= Tt[0] * Tt[1];
; #pragma unroll
;             for (int db = 0; db < 8; ++db)
; #pragma unroll
;                 for (int c = 0; c < 2; ++c) {
;                     const bf16x8 a = *(const LAS bf16x8*)(VL + (db * 16 + fr) * 144 + (32 * c + 8 * fq) * 2);
;                     o[db] = __builtin_amdgcn_mfma_f32_16x16x32_bf16(a, pf[c], o[db], 0, 0, 0);
;                 }
	v_cndmask_b32_e64 v120, v138, 1.0, s[0:1]
	v_mul_f32_e32 v121, v140, v159
	v_mul_f32_e32 v97, v120, v97
	ds_bpermute_b32 v120, v135, v121
	ds_bpermute_b32 v123, v118, v121
	ds_bpermute_b32 v122, v119, v121
	s_waitcnt lgkmcnt(3)
	v_cndmask_b32_e64 v124, 1.0, v139, s[4:5]
	v_mul_f32_e32 v124, v97, v124
	s_waitcnt lgkmcnt(2)
	v_cndmask_b32_e64 v97, 1.0, v120, s[10:11]
	s_waitcnt lgkmcnt(1)
	v_cndmask_b32_e64 v125, v123, 1.0, s[0:1]
	v_mul_f32_e32 v97, v125, v97
	s_waitcnt lgkmcnt(0)
	v_cndmask_b32_e64 v125, 1.0, v122, s[4:5]
	v_pk_mul_f32 v[120:121], v[120:121], v[122:123]
	v_mul_f32_e32 v135, v97, v125
	v_mov_b32_e32 v97, v120
	v_mov_b32_e32 v125, v121
	v_pk_mul_f32 v[140:141], v[96:97], v[124:125]
	s_nop 0
	v_mul_f32_e32 v97, v140, v141
	v_mul_f32_e32 v120, v103, v97
	v_mul_f32_e32 v101, v101, v120
	v_mul_f32_e32 v103, v142, v120
	v_mul_f32_e32 v120, v157, v97
	v_mul_f32_e32 v121, v143, v120
	v_mul_f32_e32 v120, v156, v97
	v_mul_f32_e32 v122, v144, v120
	v_mul_f32_e32 v120, v155, v97
	v_mul_f32_e32 v123, v145, v120
	v_mul_f32_e32 v120, v154, v97
	v_mul_f32_e32 v124, v146, v120
	v_mul_f32_e32 v120, v153, v97
	v_mul_f32_e32 v125, v126, v120
	v_mul_f32_e32 v120, v147, v97
	v_mul_f32_e32 v97, v127, v120
	v_cvt_pk_bf16_f32 v120, v101, v103
	v_cvt_pk_bf16_f32 v121, v121, v122
	v_cvt_pk_bf16_f32 v122, v123, v124
	v_cvt_pk_bf16_f32 v123, v125, v97
	v_mul_f32_e32 v97, v96, v135
	v_mul_f32_e32 v124, v97, v159
	v_mul_f32_e32 v101, v128, v124
	v_mul_f32_e32 v103, v129, v124
	v_mul_f32_e32 v124, v97, v158
	v_mul_f32_e32 v125, v130, v124
	v_mul_f32_e32 v124, v97, v148
	v_mul_f32_e32 v126, v131, v124
	v_mul_f32_e32 v124, v97, v149
	v_mul_f32_e32 v127, v132, v124
	v_mul_f32_e32 v124, v97, v150
	v_mul_f32_e32 v128, v133, v124
	v_mul_f32_e32 v124, v97, v152
	v_mul_f32_e32 v129, v134, v124
	v_mul_f32_e32 v124, v151, v97
	v_mul_f32_e32 v97, v99, v124
	v_cvt_pk_bf16_f32 v124, v101, v103
	v_cvt_pk_bf16_f32 v125, v125, v126
	v_cvt_pk_bf16_f32 v126, v127, v128
	v_cvt_pk_bf16_f32 v127, v129, v97
	ds_read_b128 v[128:131], v117 offset:17408
	ds_read_b128 v[132:135], v117 offset:17472
	s_waitcnt lgkmcnt(1)
	v_mfma_f32_16x16x32_bf16 v[60:63], v[128:131], v[120:123], v[60:63]
	ds_read_b128 v[128:131], v117 offset:19712
	s_waitcnt lgkmcnt(1)
	v_mfma_f32_16x16x32_bf16 v[60:63], v[132:135], v[124:127], v[60:63]
	ds_read_b128 v[132:135], v117 offset:19776
	s_waitcnt lgkmcnt(1)
	v_mfma_f32_16x16x32_bf16 v[72:75], v[128:131], v[120:123], v[72:75]
	ds_read_b128 v[128:131], v117 offset:22016
	s_waitcnt lgkmcnt(1)
	v_mfma_f32_16x16x32_bf16 v[72:75], v[132:135], v[124:127], v[72:75]
	ds_read_b128 v[132:135], v117 offset:22080
	s_waitcnt lgkmcnt(1)
	v_mfma_f32_16x16x32_bf16 v[56:59], v[128:131], v[120:123], v[56:59]
	ds_read_b128 v[128:131], v117 offset:24320
	s_waitcnt lgkmcnt(1)
	v_mfma_f32_16x16x32_bf16 v[56:59], v[132:135], v[124:127], v[56:59]
	ds_read_b128 v[132:135], v117 offset:24384
	s_waitcnt lgkmcnt(1)
	v_mfma_f32_16x16x32_bf16 v[44:47], v[128:131], v[120:123], v[44:47]
	ds_read_b128 v[128:131], v117 offset:26624
	s_waitcnt lgkmcnt(1)
	v_mfma_f32_16x16x32_bf16 v[44:47], v[132:135], v[124:127], v[44:47]
	ds_read_b128 v[132:135], v117 offset:26688
	s_waitcnt lgkmcnt(1)
	v_mfma_f32_16x16x32_bf16 v[32:35], v[128:131], v[120:123], v[32:35]
	ds_read_b128 v[128:131], v117 offset:28928
	s_waitcnt lgkmcnt(1)
	v_mfma_f32_16x16x32_bf16 v[32:35], v[132:135], v[124:127], v[32:35]
	ds_read_b128 v[132:135], v117 offset:28992
	s_waitcnt lgkmcnt(1)
	v_mfma_f32_16x16x32_bf16 v[24:27], v[128:131], v[120:123], v[24:27]
	ds_read_b128 v[128:131], v117 offset:31232
	s_waitcnt lgkmcnt(1)
	v_mfma_f32_16x16x32_bf16 v[24:27], v[132:135], v[124:127], v[24:27]
	ds_read_b128 v[132:135], v117 offset:31296
	s_waitcnt lgkmcnt(1)
	v_mfma_f32_16x16x32_bf16 v[20:23], v[128:131], v[120:123], v[20:23]
	ds_read_b128 v[128:131], v117 offset:33536
	s_waitcnt lgkmcnt(1)
	v_mfma_f32_16x16x32_bf16 v[20:23], v[132:135], v[124:127], v[20:23]
	ds_read_b128 v[132:135], v117 offset:33600
	s_waitcnt lgkmcnt(1)
	v_mfma_f32_16x16x32_bf16 v[16:19], v[128:131], v[120:123], v[16:19]
	v_mul_f32_e64 v120, v136, v138
	v_mul_f32_e64 v121, v137, v139
	v_mul_f32_e32 v97, v120, v121
	s_waitcnt lgkmcnt(0)
	v_mfma_f32_16x16x32_bf16 v[16:19], v[132:135], v[124:127], v[16:19]
	v_mul_f32_e32 v97, v97, v141
	v_mul_f32_e32 v96, v96, v97
